# grid barrier: all workgroups poll the top arrival counter directly (no per-XCD generation hop)
# baseline (speedup 1.0000x reference)
.LBB0_122:
	s_or_b64 exec, exec, s[10:11]
	v_cvt_f32_u32_e32 v4, v2
	s_waitcnt vmcnt(0)
	v_readfirstlane_b32 s2, v3
	v_sub_u32_e32 v3, 0, v2
	v_rcp_iflag_f32_e32 v4, v4
	v_add_u32_e32 v5, s2, v1
	v_mul_f32_e32 v4, 0x4f7ffffe, v4
	v_cvt_u32_f32_e32 v4, v4
	v_mul_lo_u32 v1, v3, v4
	v_mul_hi_u32 v1, v4, v1
	v_add_u32_e32 v1, v4, v1
	v_mul_hi_u32 v1, v5, v1
	v_mul_lo_u32 v3, v1, v2
	v_sub_u32_e32 v3, v5, v3
	v_add_u32_e32 v4, 1, v1
	v_cmp_ge_u32_e32 vcc, v3, v2
	s_nop 1
	v_cndmask_b32_e32 v1, v1, v4, vcc
	v_sub_u32_e32 v4, v3, v2
	v_cndmask_b32_e32 v3, v3, v4, vcc
	v_add_u32_e32 v4, 1, v1
	v_cmp_ge_u32_e32 vcc, v3, v2
	v_add_u32_e32 v3, 1, v5
	s_nop 0
	v_cndmask_b32_e32 v1, v1, v4, vcc
	v_mul_lo_u32 v4, v2, v1
	v_add_u32_e32 v2, v4, v2
	s_waitcnt lgkmcnt(0)
	v_add_u32_e32 v4, 1, v1
	v_mul_lo_u32 v4, v4, v0
	v_readlane_b32 s14, v252, 2
	v_readlane_b32 s15, v252, 3
	s_add_u32 s14, s14, 0x3400
	s_addc_u32 s15, s15, 0
	v_mov_b32_e32 v6, 0
	v_cmp_ne_u32_e32 vcc, v3, v2
	s_cbranch_vccnz .Lxb_wait_0
	buffer_wbl2 sc1
	s_waitcnt vmcnt(0)
	v_mov_b32_e32 v5, 1
	global_atomic_add v6, v5, s[14:15]
.Lxb_wait_0:
	buffer_inv sc1
	s_mov_b32 s16, 0
.Lxb_spin_0:
	global_load_dword v5, v6, s[14:15] sc1
	s_add_u32 s16, s16, 1
	s_waitcnt vmcnt(0)
	v_cmp_ge_u32_e32 vcc, v5, v4
	s_cbranch_vccnz .Lxb_done_0
	s_cmp_lt_u32 s16, 0x200000
	s_cbranch_scc0 .Lxb_done_0
	s_sleep 1
	s_branch .Lxb_spin_0
.Lxb_done_0:
.LBB0_155:
	s_or_b64 exec, exec, s[4:5]
	s_load_dword s2, s[92:93], 0x134
	s_load_dwordx2 s[10:11], s[92:93], 0x118
	v_mov_b32_e32 v148, v174
	s_mov_b64 s[20:21], s[80:81]
	s_mov_b32 s4, 0
	s_waitcnt lgkmcnt(0)
	s_barrier
	s_ashr_i32 s5, s4, 31
	s_add_u32 s22, s92, s4
	s_addc_u32 s23, s93, s5
	s_add_u32 s24, s20, 0x4540000
	v_writelane_b32 v252, s2, 6
	s_waitcnt vmcnt(0)
	v_mov_b32_e32 v0, 0
	s_mov_b32 s3, s88
	s_mov_b32 s2, s86
	s_addc_u32 s25, s21, 0
	s_cmpk_gt_i32 s3, 0x17f
	v_mov_b32_e32 v97, 0
	s_cbranch_scc1 .LBB0_194
	s_load_dwordx2 s[6:7], s[22:23], 0x58
	s_load_dwordx4 s[12:15], s[22:23], 0x0
	s_add_u32 s26, s20, 0x3b40000
	s_addc_u32 s27, s21, 0
	v_and_b32_e32 v1, 63, v148
	s_waitcnt lgkmcnt(0)
	s_cmp_lg_u64 s[6:7], 0
	s_cselect_b64 s[28:29], -1, 0
	s_add_u32 s16, s20, 0x4552000
	s_addc_u32 s4, s21, 0
	s_cmp_lg_u64 s[12:13], 0
	v_ashrrev_i32_e32 v3, 4, v148
	s_cselect_b64 s[8:9], -1, 0
	v_lshlrev_b32_e32 v98, 3, v1
	v_lshlrev_b32_e32 v0, 4, v1
	s_and_b32 s17, s4, 0xffff
	v_cmp_eq_u32_e64 s[4:5], 0, v1
	v_lshlrev_b32_e32 v96, 5, v1
	v_mov_b32_e32 v1, v97
	v_lshl_add_u64 v[104:105], s[10:11], 0, v[0:1]
	v_lshlrev_b32_e32 v1, 11, v3
	v_and_b32_e32 v1, 0xffffe000, v1
	v_lshl_add_u64 v[100:101], s[6:7], 0, v[96:97]
	v_lshl_add_u32 v1, s3, 16, v1
	s_movk_i32 s6, 0x1c00
	v_and_b32_e32 v5, -4, v3
	v_or_b32_e32 v2, 4, v98
	v_or_b32_e32 v4, 0x200, v98
	v_or_b32_e32 v6, 0x204, v98
	v_or3_b32 v99, v1, v0, s6
	v_cndmask_b32_e64 v0, 0, 1, s[8:9]
	s_mov_b32 s19, 0x20000
	s_brev_b32 s18, -2
	v_lshl_add_u64 v[102:103], s[10:11], 0, v[96:97]
	v_lshl_add_u32 v106, s3, 5, v5
	s_lshl_b32 s33, s2, 5
	s_lshl_b32 s35, s2, 16
	v_cmp_ne_u32_e64 s[6:7], 1, v0
	s_movk_i32 s37, 0x1000
	s_movk_i32 s38, 0xfff
	s_movk_i32 s39, 0x6000
	s_mov_b64 s[30:31], 0x1000
	v_lshlrev_b32_e32 v108, 2, v2
	v_lshlrev_b32_e32 v110, 2, v4
	v_lshlrev_b32_e32 v112, 2, v6
	s_mov_b32 s34, 0x3a800000
	s_mov_b32 s36, 0x358637bd
	s_mov_b32 s42, 0x800000
	v_mov_b32_e32 v118, 1
	v_lshlrev_b32_e32 v96, 2, v98
	s_mov_b32 s43, s3
	s_branch .LBB0_159

.Lxb_done_1:
.LBB0_462:
	s_or_b64 exec, exec, s[4:5]
	v_mov_b32_e32 v50, v174
	s_mov_b64 s[66:67], s[80:81]
	s_load_dwordx2 s[14:15], s[92:93], 0x118
	s_waitcnt lgkmcnt(0)
	s_barrier
	s_mov_b32 s74, 0
	s_add_u32 s68, s66, 0x5d52000
	s_addc_u32 s69, s67, 0
	s_ashr_i32 s77, s74, 31
	s_add_u32 s2, s92, s74
	s_waitcnt vmcnt(0)
	v_mov_b32_e32 v0, 0
	s_mov_b32 s75, s88
	s_mov_b32 s76, s86
	s_addc_u32 s3, s93, s77
	s_load_dwordx2 s[10:11], s[2:3], 0xa0
	s_add_u32 s12, s66, 0xb932000
	s_addc_u32 s13, s67, 0
	s_add_i32 s2, s76, s75
	v_mov_b32_e32 v25, 0
	s_cmpk_gt_i32 s2, 0x8ff
	v_lshlrev_b32_e32 v42, 3, v50
	s_mov_b32 s3, s75
	s_cbranch_scc1 .LBB0_477
	v_and_b32_e32 v26, 0xf8, v42
	s_lshl_b32 s20, s76, 1
	s_lshl_b32 s21, s2, 9
	s_lshl_b32 s22, s76, 10
	s_lshl_b32 s23, s2, 12
	s_lshl_b32 s24, s76, 13
	s_lshl_b32 s25, s75, 9
	s_lshl_b32 s26, s75, 12
	s_mov_b32 s27, 0x2aaaaaab
	s_mov_b32 s28, 0x5ffff
	v_mov_b32_e32 v27, 0xff
	v_mov_b32_e32 v35, 0x7ff
	s_movk_i32 s29, 0x1660
	v_mov_b64_e32 v[28:29], s[68:69]
	s_movk_i32 s30, 0xfd00
	s_mov_b64 s[16:17], 0x840
	s_movk_i32 s31, 0x1000
	s_movk_i32 s33, 0xffa0
	s_mov_b64 s[18:19], 0x1800
	s_mov_b32 s34, 0x800000
	s_mov_b32 s35, 0x600000
	v_mov_b32_e32 v43, 0x3e000000
	v_mov_b32_e32 v44, v42
	v_mov_b32_e32 v45, v50
	s_mov_b32 s3, s75
	s_branch .LBB0_465

.Lxb_done_2:
.LBB0_938:
	s_or_b64 exec, exec, s[4:5]
	v_mov_b32_e32 v96, v174
	s_mov_b64 s[8:9], s[80:81]
	s_load_dwordx2 s[2:3], s[92:93], 0x118
	s_waitcnt lgkmcnt(0)
	s_barrier
	s_mov_b32 s2, 0
	v_mov_b32_e32 v0, 0
	s_mov_b32 s2, s88
	s_mov_b32 s3, s86
	v_mov_b32_e32 v73, 0
	s_mov_b32 s11, 0
	s_cmpk_gt_i32 s2, 0x17f
	v_mbcnt_lo_u32_b32 v175, -1, 0
	s_cbranch_scc1 .LBB0_1129
	s_add_u32 s33, s8, 0xb932000
	s_addc_u32 s36, s9, 0
	s_add_u32 s37, s8, 0xbf32000
	s_addc_u32 s38, s9, 0
	s_add_u32 s12, s8, 0xd192000
	s_addc_u32 s13, s9, 0
	s_add_u32 s14, s8, 0xd132000
	s_addc_u32 s15, s9, 0
	s_add_u32 s16, s8, 0xe3f2000
	s_addc_u32 s17, s9, 0
	s_add_u32 s18, s8, 0xeff2000
	s_addc_u32 s19, s9, 0
	s_add_u32 s20, s8, 0xfbf2000
	s_addc_u32 s21, s9, 0
	s_add_u32 s22, s8, 0xfc52000
	s_addc_u32 s23, s9, 0
	s_add_u32 s24, s8, 0x8752000
	s_addc_u32 s25, s9, 0
	s_add_u32 s26, s8, 0x7b52000
	v_mov_b32_e32 v1, v0
	v_mov_b32_e32 v2, v0
	v_mov_b32_e32 v3, v0
	s_addc_u32 s27, s9, 0
	s_lshl_b32 s39, s2, 2
	s_lshl_b32 s40, s3, 2
	s_movk_i32 s41, 0x800
	s_movk_i32 s42, 0x1000
	s_movk_i32 s43, 0xffef
	s_movk_i32 s44, 0xffdf
	s_movk_i32 s45, 0xffcf
	s_movk_i32 s46, 0x5600
	s_movk_i32 s47, 0xffee
	s_movk_i32 s48, 0xffed
	s_movk_i32 s49, 0xffec
	s_movk_i32 s50, 0xffde
	s_movk_i32 s51, 0xffdd
	s_movk_i32 s52, 0xffdc
	s_movk_i32 s53, 0xffce
	s_movk_i32 s54, 0xffcd
	s_movk_i32 s55, 0xffcc
	s_movk_i32 s56, 0xffeb
	s_movk_i32 s57, 0xffea
	s_movk_i32 s58, 0xffe9
	s_movk_i32 s59, 0xffe8
	s_movk_i32 s60, 0xffe7
	s_movk_i32 s61, 0xffe6
	s_movk_i32 s62, 0xffe5
	s_movk_i32 s63, 0xffe4
	s_movk_i32 s64, 0xffe3
	s_movk_i32 s65, 0xffe2
	s_movk_i32 s66, 0xffe1
	s_movk_i32 s67, 0xffe0
	s_movk_i32 s68, 0x110
	s_movk_i32 s69, 0xfef4
	s_movk_i32 s70, 0x1100
	s_movk_i32 s71, 0x7fff
	v_mbcnt_hi_u32_b32 v97, -1, v175
	v_mov_b32_e32 v204, v73
	v_mov_b32_e32 v205, v73
	v_mov_b32_e32 v200, v73
	v_mov_b32_e32 v201, v73
	v_mov_b32_e32 v202, v73
	v_mov_b32_e32 v203, v73
	s_mov_b32 s72, s2
	s_branch .LBB0_941

.Lxb_done_3:
.LBB0_1191:
	s_or_b64 exec, exec, s[4:5]
	s_load_dwordx2 s[2:3], s[92:93], 0x118
	s_load_dword s6, s[92:93], 0x134
	v_mov_b32_e32 v176, v174
	s_mov_b64 s[42:43], s[80:81]
	s_mov_b32 s79, 0
	s_waitcnt lgkmcnt(0)
	v_mov_b32_e32 v0, 0
	s_mov_b32 s80, s88
	s_mov_b32 s4, s86
	s_barrier
	s_cmpk_lt_i32 s80, 0x80
	s_cselect_b64 s[4:5], -1, 0
	s_lshl_b32 s6, s6, 5
	s_ashr_i32 s7, s6, 31
	v_writelane_b32 v252, s4, 7
	s_lshl_b64 s[8:9], s[6:7], 2
	s_add_u32 s6, s42, s8
	v_writelane_b32 v252, s5, 8
	v_writelane_b32 v252, s8, 9
	s_addc_u32 s7, s43, s9
	s_add_u32 s6, s6, 0x453f800
	v_writelane_b32 v252, s9, 10
	v_writelane_b32 v252, s6, 11
	s_addc_u32 s6, s7, 0
	s_add_u32 s75, s42, 0xa432000
	s_addc_u32 s66, s43, 0
	s_add_u32 s81, s42, 0x5d52000
	s_addc_u32 s84, s43, 0
	s_add_u32 s85, s42, 0xa372000
	s_addc_u32 s86, s43, 0
	s_add_u32 s48, s42, 0x4552000
	s_addc_u32 s49, s43, 0
	s_add_u32 s50, s42, 0xb932000
	s_addc_u32 s51, s43, 0
	s_ashr_i32 s89, s79, 31
	s_add_u32 s67, s42, 0x8752000
	s_addc_u32 s64, s43, 0
	s_add_u32 s65, s42, 0xe3f2000
	s_addc_u32 s54, s43, 0
	s_add_u32 s55, s42, 0xeff2000
	s_addc_u32 s61, s43, 0
	s_add_u32 s62, s42, 0x7b52000
	s_addc_u32 s63, s43, 0
	s_add_u32 s46, s42, 0xfbf2000
	s_addc_u32 s76, s43, 0
	s_add_u32 s77, s42, 0xfc52000
	s_addc_u32 s38, s43, 0
	v_writelane_b32 v252, s6, 12
	s_add_u32 s2, s2, 0x3d00000
	v_writelane_b32 v252, s2, 13
	s_addc_u32 s2, s3, 0
	v_writelane_b32 v252, s2, 14
	s_add_u32 s2, s42, 0x3bbc000
	v_writelane_b32 v252, s2, 15
	s_addc_u32 s2, s43, 0
	s_add_u32 s78, s42, 0xad32000
	s_addc_u32 s57, s43, 0
	v_writelane_b32 v252, s2, 16
	s_add_u32 s2, s42, 0xd1f2000
	v_writelane_b32 v252, s2, 17
	s_addc_u32 s2, s43, 0
	s_add_u32 s56, s42, 0x7552000
	s_addc_u32 s58, s43, 0
	v_writelane_b32 v252, s2, 18
	s_add_u32 s2, s42, 0x3b7c000
	v_writelane_b32 v252, s2, 19
	s_addc_u32 s2, s43, 0
	v_writelane_b32 v252, s2, 20
	s_mov_b64 s[2:3], 0
	v_mov_b32_e32 v89, 0
	s_mov_b32 s45, 0
	v_cmp_eq_u32_e64 s[4:5], 0, v176
	s_mov_b64 s[0:1], s[92:93]
	v_mov_b32_e32 v1, v0
	v_mov_b32_e32 v2, v0
	v_mov_b32_e32 v3, v0
	v_mov_b32_e32 v177, 1
	v_mov_b32_e32 v178, 0x20008
	s_movk_i32 s59, 0x1000
	s_movk_i32 s87, 0x300
	s_movk_i32 s88, 0xd0
	s_movk_i32 s95, 0xa0
	s_mov_b32 s70, 0x3e16c740
	s_mov_b32 s71, 0xff61b1e6
	s_movk_i32 s96, 0x200
	s_movk_i32 s39, 0x100
	s_movk_i32 s47, 0x800
	s_movk_i32 s97, 0x90
	s_movk_i32 s60, 0x7fff
	s_mov_b32 s82, 0xd7f2000
	s_movk_i32 s83, 0xfeff
	v_mov_b32_e32 v179, 0x4180
	v_mov_b32_e32 v180, 0x4380
	v_mov_b32_e32 v181, 0x80
	v_mov_b32_e32 v182, 0xf149f2ca
	v_mov_b32_e32 v183, 0x980
	v_mov_b32_e32 v184, 0xb80
	s_mov_b64 s[6:7], 0
	v_writelane_b32 v252, s2, 21
	s_mov_b64 s[14:15], -1
	s_mov_b64 s[52:53], 0x2000
	v_writelane_b32 v252, s3, 22
	s_branch .LBB0_1193

.Lxb_done_4:
.LBB0_1398:
	s_or_b64 exec, exec, s[4:5]
	v_mov_b32_e32 v150, v174
	s_load_dwordx2 s[2:3], s[90:91], 0x118
	s_waitcnt lgkmcnt(0)
	s_mov_b64 s[16:17], s[84:85]
	s_barrier
	s_add_u32 s18, s16, 0x4543000
	v_mov_b32_e32 v0, 0
	s_mov_b32 s70, 0
	s_mov_b32 s2, s86
	s_mov_b32 s3, s88
	s_addc_u32 s19, s17, 0
	s_cmpk_eq_i32 s2, 0x100
	s_mov_b64 s[4:5], -1
	s_cbranch_scc1 .LBB0_1413
	s_cmpk_gt_i32 s3, 0x6bf
	s_cbranch_scc1 .LBB0_1412
	v_and_b32_e32 v10, 63, v150
	v_mov_b32_e32 v3, 0
	v_lshlrev_b32_e32 v2, 3, v10
	v_lshl_add_u64 v[8:9], s[16:17], 0, v[2:3]
	v_lshlrev_b32_e32 v2, 2, v150
	s_mov_b64 s[4:5], 0x6952000
	s_waitcnt vmcnt(0)
	v_and_b32_e32 v22, 60, v2
	v_lshlrev_b32_e32 v2, 3, v150
	v_lshl_add_u64 v[4:5], v[8:9], 0, s[4:5]
	s_mov_b64 s[4:5], 0x6f52000
	v_and_b32_e32 v14, 56, v2
	v_lshl_add_u64 v[6:7], v[8:9], 0, s[4:5]
	s_mov_b64 s[4:5], 0xcb32000
	v_lshlrev_b32_e32 v2, 1, v14
	v_lshlrev_b32_e32 v20, 2, v10
	v_lshl_add_u64 v[8:9], v[8:9], 0, s[4:5]
	v_cmp_eq_u32_e64 s[4:5], 0, v10
	v_lshl_add_u64 v[10:11], s[16:17], 0, v[2:3]
	s_mov_b64 s[6:7], 0x7552000
	v_ashrrev_i32_e32 v2, 3, v150
	s_movk_i32 s8, 0x6000
	v_lshl_add_u64 v[10:11], v[10:11], 0, s[6:7]
	v_mad_i64_i32 v[12:13], s[6:7], v2, s8, 0
	v_lshlrev_b32_e32 v21, 1, v2
	v_add_u32_e32 v2, 0x200, v150
	v_add_u32_e32 v24, 0x400, v150
	v_add_u32_e32 v25, 0x600, v150
	s_ashr_i32 s24, s70, 31
	v_ashrrev_i32_e32 v16, 3, v2
	v_ashrrev_i32_e32 v18, 3, v24
	v_ashrrev_i32_e32 v26, 3, v25
	v_mul_u32_u24_e32 v23, 0x210, v14
	v_mad_i64_i32 v[14:15], s[6:7], v16, s8, 0
	v_lshlrev_b32_e32 v32, 1, v16
	v_mad_i64_i32 v[16:17], s[6:7], v18, s8, 0
	v_lshlrev_b32_e32 v33, 1, v18
	v_mad_i64_i32 v[18:19], s[6:7], v26, s8, 0
	v_lshlrev_b32_e32 v34, 1, v26
	s_add_u32 s12, s16, 0x4552000
	v_lshlrev_b32_e32 v26, 4, v150
	s_movk_i32 s9, 0x210
	s_addc_u32 s6, s17, 0
	v_and_b32_e32 v38, 0x1f0, v26
	v_ashrrev_i32_e32 v28, 5, v150
	v_ashrrev_i32_e32 v2, 5, v2
	v_ashrrev_i32_e32 v26, 5, v24
	v_ashrrev_i32_e32 v24, 5, v25
	v_ashrrev_i32_e32 v0, 6, v150
	s_and_b32 s13, s6, 0xffff
	v_mul_lo_u32 v35, v28, s9
	v_mul_lo_u32 v36, v2, s9
	v_mul_lo_u32 v37, v26, s9
	v_mul_lo_u32 v39, v24, s9
	s_lshl_b32 s6, s3, 3
	v_lshl_or_b32 v25, s3, 17, v38
	v_ashrrev_i32_e32 v1, 31, v0
	s_mov_b32 s21, 0
	s_mov_b32 s15, 0x20000
	s_brev_b32 s14, -2
	s_add_i32 s20, s6, 0xfffffa00
	s_lshl_b32 s25, s2, 3
	v_lshlrev_b32_e32 v24, 11, v24
	v_or_b32_e32 v25, 0x600, v25
	s_lshl_b32 s26, s2, 17
	v_lshlrev_b32_e32 v26, 11, v26
	v_lshlrev_b32_e32 v27, 11, v2
	v_lshlrev_b32_e32 v28, 11, v28
	s_lshl_b32 s22, s3, 6
	s_lshl_b32 s27, s2, 6
	s_lshl_b32 s28, s3, 4
	s_lshl_b32 s29, s2, 4
	v_lshlrev_b32_e32 v29, 2, v22
	v_mov_b32_e32 v30, 0x358637bd
	s_mov_b32 s30, 0x800000
	v_lshlrev_b32_e32 v2, 1, v20
	v_add_u32_e32 v31, v21, v23
	v_add_u32_e32 v32, v32, v23
	v_add_u32_e32 v33, v33, v23
	v_add_u32_e32 v34, v34, v23
	v_add_u32_e32 v35, v38, v35
	v_add_u32_e32 v36, v38, v36
	v_add_u32_e32 v37, v38, v37
	v_add_u32_e32 v38, v38, v39
	v_mov_b32_e32 v39, 1
	s_mov_b32 s31, s3
	s_branch .LBB0_1402

.Lxb_done_5:
.LBB0_1679:
	s_or_b64 exec, exec, s[4:5]
	v_mov_b32_e32 v59, v174
	s_load_dwordx2 s[18:19], s[90:91], 0x118
	s_mov_b64 s[10:11], s[84:85]
	s_waitcnt lgkmcnt(0)
	s_barrier
	s_add_u32 s16, s10, 0x4546000
	s_mov_b32 s4, 0
	s_waitcnt vmcnt(0)
	v_mov_b32_e32 v0, 0
	s_mov_b32 s2, s86
	s_mov_b32 s3, s88
	s_addc_u32 s17, s11, 0
	s_cmpk_gt_i32 s3, 0x17f
	v_mov_b32_e32 v57, 0
	s_cbranch_scc1 .LBB0_1702
	s_ashr_i32 s5, s4, 31
	s_add_u32 s8, s90, s4
	s_addc_u32 s9, s91, s5
	s_load_dwordx4 s[4:7], s[8:9], 0x60
	v_and_b32_e32 v2, 63, v59
	s_add_u32 s20, s10, 0x3b40000
	s_addc_u32 s21, s11, 0
	v_lshlrev_b32_e32 v56, 5, v2
	s_waitcnt lgkmcnt(0)
	s_cmp_lg_u64 s[6:7], 0
	v_lshl_add_u64 v[68:69], s[6:7], 0, v[56:57]
	s_load_dword s6, s[90:91], 0x134
	s_cselect_b64 s[22:23], -1, 0
	s_add_u32 s12, s10, 0x4552000
	v_lshlrev_b32_e32 v60, 4, v2
	v_mov_b32_e32 v61, v57
	s_addc_u32 s13, s11, 0
	v_lshl_add_u64 v[0:1], s[10:11], 0, v[60:61]
	s_mov_b64 s[8:9], 0xe3f2000
	v_ashrrev_i32_e32 v3, 4, v59
	v_lshl_add_u64 v[62:63], v[0:1], 0, s[8:9]
	v_lshl_add_u64 v[64:65], s[4:5], 0, v[56:57]
	v_lshl_add_u64 v[0:1], s[10:11], 0, v[56:57]
	s_mov_b64 s[4:5], 0x3b42000
	s_and_b32 s13, s13, 0xffff
	v_lshl_add_u64 v[66:67], v[0:1], 0, s[4:5]
	s_waitcnt lgkmcnt(0)
	s_cmp_eq_u32 s6, 0
	v_lshlrev_b32_e32 v1, 11, v3
	v_lshlrev_b32_e32 v58, 3, v2
	s_cselect_b64 s[6:7], -1, 0
	v_and_b32_e32 v1, 0xffffe000, v1
	v_and_b32_e32 v5, -4, v3
	v_cmp_eq_u32_e64 s[4:5], 0, v2
	v_or_b32_e32 v0, 4, v58
	v_or_b32_e32 v2, 0x200, v58
	v_or_b32_e32 v4, 0x204, v58
	v_cndmask_b32_e64 v70, 0, 1.0, s[6:7]
	v_lshl_add_u32 v1, s3, 16, v1
	s_movk_i32 s6, 0x1c00
	s_mov_b32 s15, 0x20000
	s_brev_b32 s14, -2
	v_mov_b32_e32 v71, v70
	v_lshl_add_u64 v[72:73], s[18:19], 0, v[60:61]
	v_lshl_add_u32 v74, s3, 5, v5
	s_lshl_b32 s25, s2, 5
	v_or3_b32 v81, v1, v60, s6
	s_lshl_b32 s27, s2, 16
	v_lshlrev_b32_e32 v76, 1, v58
	v_mov_b32_e32 v77, v57
	s_movk_i32 s33, 0xfff
	s_movk_i32 s36, 0x6000
	v_mov_b32_e32 v78, v70
	v_mov_b32_e32 v79, v70
	s_mov_b32 s24, 0x3a800000
	s_mov_b32 s26, 0x358637bd
	v_mov_b32_e32 v80, 0x358637bd
	s_mov_b32 s37, 0x800000
	s_mov_b64 s[28:29], 0x4000
	s_mov_b64 s[30:31], 0x3000
	v_lshlrev_b32_e32 v82, 2, v0
	v_lshlrev_b32_e32 v84, 2, v2
	v_lshlrev_b32_e32 v86, 2, v4
	v_mov_b32_e32 v170, 1
	s_mov_b32 s38, s3
	s_branch .LBB0_1683

.Lxb_done_6:
.LBB0_1835:
	s_or_b64 exec, exec, s[4:5]
	v_mov_b32_e32 v158, v174
	s_mov_b64 s[8:9], s[84:85]
	s_load_dwordx2 s[2:3], s[90:91], 0x118
	s_waitcnt lgkmcnt(0)
	s_barrier
	v_mov_b32_e32 v0, 0
	s_mov_b32 s2, 0
	s_mov_b32 s39, s88
	s_mov_b32 s3, s86
	s_cmpk_lt_i32 s39, 0xc0
	s_cselect_b64 s[4:5], -1, 0
	s_cmpk_gt_i32 s39, 0xbf
	s_cselect_b64 s[10:11], -1, 0
	v_readfirstlane_b32 s33, v158
	s_and_b64 vcc, exec, s[10:11]
	s_barrier
	s_cbranch_vccnz .LBB0_1837
	s_ashr_i32 s6, s39, 31
	s_lshr_b32 s6, s6, 29
	s_add_i32 s6, s39, s6
	s_ashr_i32 s7, s6, 3
	s_and_b32 s6, s6, -8
	s_sub_i32 s6, s39, s6
	s_lshr_b32 s12, s6, 31
	s_or_b32 s12, s12, 24
	s_mul_i32 s6, s12, s6
	s_add_i32 s6, s6, s7
	s_ashr_i32 s7, s6, 31
	s_lshr_b32 s7, s7, 27
	s_add_i32 s7, s6, s7
	s_ashr_i32 s12, s7, 5
	s_lshl_b32 s12, s12, 3
	s_sub_i32 s13, 48, s12
	s_min_u32 s13, s13, 8
	s_andn2_b32 s7, s7, 31
	s_sub_i32 s14, s6, s7
	v_cvt_f32_ubyte0_e32 v1, s13
	v_cvt_f32_i32_e32 v0, s14
	v_rcp_iflag_f32_e32 v2, v1
	s_ashr_i32 s6, s14, 30
	s_or_b32 s15, s6, 1
	v_mul_f32_e32 v2, v0, v2
	v_trunc_f32_e32 v2, v2
	v_fma_f32 v0, -v2, v1, v0
	v_cvt_i32_f32_e32 v2, v2
	v_cmp_ge_f32_e64 s[6:7], |v0|, v1
	s_and_b64 s[6:7], s[6:7], exec
	s_cselect_b32 s6, s15, 0
	v_readfirstlane_b32 s7, v2
	s_add_i32 s7, s7, s6
	s_sext_i32_i8 s6, s7
	s_mul_i32 s7, s7, s13
	s_sub_i32 s7, s14, s7
	s_sext_i32_i8 s7, s7
	s_add_i32 s20, s12, s7

.Lxb_done_7:
.LBB0_2069:
	s_or_b64 exec, exec, s[4:5]
	v_mov_b32_e32 v59, v174
	s_mov_b64 s[10:11], s[84:85]
	s_load_dwordx2 s[18:19], s[90:91], 0x118
	s_waitcnt lgkmcnt(0)
	s_barrier
	s_add_u32 s16, s10, 0x4549000
	s_mov_b32 s4, 0
	s_waitcnt vmcnt(0)
	v_mov_b32_e32 v0, 0
	s_mov_b32 s2, s88
	s_mov_b32 s3, s86
	s_addc_u32 s17, s11, 0
	s_cmpk_gt_i32 s2, 0x17f
	v_mov_b32_e32 v57, 0
	s_cbranch_scc1 .LBB0_2092
	s_ashr_i32 s5, s4, 31
	s_add_u32 s4, s90, s4
	s_addc_u32 s5, s91, s5
	s_load_dwordx2 s[6:7], s[4:5], 0x58
	s_add_u32 s20, s10, 0x3b40000
	s_load_dwordx2 s[4:5], s[4:5], 0x70
	v_and_b32_e32 v2, 63, v59
	s_addc_u32 s21, s11, 0
	v_lshlrev_b32_e32 v60, 4, v2
	v_mov_b32_e32 v61, v57
	s_waitcnt lgkmcnt(0)
	s_cmp_lg_u64 s[6:7], 0
	v_lshl_add_u64 v[0:1], s[10:11], 0, v[60:61]
	s_mov_b64 s[8:9], 0xbd52000
	v_lshlrev_b32_e32 v56, 5, v2
	s_cselect_b64 s[22:23], -1, 0
	s_add_u32 s6, s6, 0x1000
	v_lshlrev_b32_e32 v58, 3, v2
	v_lshl_add_u64 v[62:63], v[0:1], 0, s[8:9]
	v_lshl_add_u64 v[64:65], s[4:5], 0, v[56:57]
	v_lshl_add_u64 v[0:1], s[10:11], 0, v[56:57]
	s_mov_b64 s[4:5], 0x3b45000
	s_addc_u32 s7, s7, 0
	v_lshl_add_u64 v[66:67], v[0:1], 0, s[4:5]
	v_cmp_eq_u32_e64 s[4:5], 0, v2
	v_or_b32_e32 v2, 0x200, v58
	v_lshl_add_u64 v[68:69], s[6:7], 0, v[56:57]
	v_lshlrev_b32_e32 v56, 2, v2
	v_lshl_add_u64 v[70:71], s[6:7], 0, v[56:57]
	s_load_dword s6, s[90:91], 0x134
	s_add_u32 s12, s10, 0x4552000
	s_addc_u32 s13, s11, 0
	v_ashrrev_i32_e32 v3, 4, v59
	s_and_b32 s13, s13, 0xffff
	s_waitcnt lgkmcnt(0)
	s_cmp_eq_u32 s6, 0
	v_lshlrev_b32_e32 v1, 11, v3
	s_cselect_b64 s[6:7], -1, 0
	v_and_b32_e32 v1, 0xffffe000, v1
	v_and_b32_e32 v5, -4, v3
	v_or_b32_e32 v0, 4, v58
	v_or_b32_e32 v4, 0x204, v58
	v_cndmask_b32_e64 v72, 0, 1.0, s[6:7]
	v_lshl_add_u32 v1, s2, 16, v1
	s_movk_i32 s6, 0x1c00
	s_mov_b64 s[24:25], 0x1000
	s_mov_b32 s15, 0x20000
	s_brev_b32 s14, -2
	v_mov_b32_e32 v73, v72
	v_lshl_add_u64 v[74:75], s[18:19], 0, v[60:61]
	v_lshl_add_u32 v76, s2, 5, v5
	s_lshl_b32 s27, s3, 5
	v_or3_b32 v83, v1, v60, s6
	s_lshl_b32 s29, s3, 16
	v_lshlrev_b32_e32 v78, 1, v58
	v_mov_b32_e32 v79, v57
	s_movk_i32 s33, 0xfff
	s_movk_i32 s34, 0x6000
	v_mov_b32_e32 v80, v72
	v_mov_b32_e32 v81, v72
	s_mov_b32 s26, 0x3a800000
	s_mov_b32 s28, 0x358637bd
	v_mov_b32_e32 v82, 0x358637bd
	s_mov_b32 s35, 0x800000
	v_lshlrev_b32_e32 v84, 2, v0
	v_lshlrev_b32_e32 v86, 2, v2
	v_lshlrev_b32_e32 v88, 2, v4
	v_mov_b32_e32 v172, 1
	s_mov_b32 s36, s2
	s_branch .LBB0_2073

.Lxb_done_8:
.LBB0_2219:
	s_or_b64 exec, exec, s[4:5]
	v_mov_b32_e32 v50, v174
	s_mov_b64 s[68:69], s[84:85]
	s_load_dwordx2 s[14:15], s[90:91], 0x118
	s_waitcnt lgkmcnt(0)
	s_barrier
	s_mov_b32 s76, 0
	s_add_u32 s70, s68, 0x5d52000
	s_addc_u32 s71, s69, 0
	s_ashr_i32 s80, s76, 31
	s_add_u32 s2, s90, s76
	v_mov_b32_e32 v0, 0
	s_mov_b32 s77, s88
	s_mov_b32 s79, s86
	s_addc_u32 s3, s91, s80
	s_load_dwordx2 s[2:3], s[2:3], 0xa0
	v_mov_b32_e32 v25, 0
	v_lshlrev_b32_e32 v42, 3, v50
	s_waitcnt lgkmcnt(0)
	s_add_u32 s10, s2, 0x2400
	s_addc_u32 s11, s3, 0
	s_add_u32 s12, s68, 0xb932000
	s_addc_u32 s13, s69, 0
	s_add_i32 s2, s79, s77
	s_cmpk_gt_i32 s2, 0x8ff
	s_mov_b32 s3, s77
	s_cbranch_scc1 .LBB0_2234
	v_and_b32_e32 v26, 0xf8, v42
	s_lshl_b32 s20, s79, 1
	s_lshl_b32 s21, s2, 9
	s_lshl_b32 s22, s79, 10
	s_lshl_b32 s23, s2, 12
	s_lshl_b32 s24, s79, 13
	s_lshl_b32 s25, s77, 9
	s_lshl_b32 s26, s77, 12
	s_mov_b32 s27, 0x2aaaaaab
	s_mov_b32 s28, 0x5ffff
	v_mov_b32_e32 v27, 0xff
	v_mov_b32_e32 v35, 0x7ff
	s_movk_i32 s29, 0x1660
	v_mov_b64_e32 v[28:29], s[70:71]
	s_movk_i32 s30, 0xfd00
	s_mov_b64 s[16:17], 0x840
	s_movk_i32 s31, 0x1000
	s_movk_i32 s33, 0xffa0
	s_mov_b64 s[18:19], 0x1800
	s_mov_b32 s34, 0x800000
	s_mov_b32 s35, 0x600000
	v_mov_b32_e32 v43, 0x3e000000
	v_mov_b32_e32 v44, v42
	v_mov_b32_e32 v45, v50
	s_mov_b32 s3, s77
	s_branch .LBB0_2222

.Lxb_done_9:
.LBB0_2695:
	s_or_b64 exec, exec, s[4:5]
	v_mov_b32_e32 v96, v174
	s_mov_b64 s[8:9], s[82:83]
	s_load_dwordx2 s[2:3], s[90:91], 0x118
	s_waitcnt lgkmcnt(0)
	s_barrier
	s_mov_b32 s2, 0
	v_mov_b32_e32 v0, 0
	s_mov_b32 s2, s88
	s_mov_b32 s3, s86
	v_mov_b32_e32 v73, 0
	s_cmpk_gt_i32 s2, 0x17f
	s_mov_b32 s11, 0
	s_cbranch_scc1 .LBB0_2886
	s_add_u32 s33, s8, 0xb932000
	s_addc_u32 s36, s9, 0
	s_add_u32 s37, s8, 0xbf32000
	s_addc_u32 s38, s9, 0
	s_add_u32 s12, s8, 0xd192000
	s_addc_u32 s13, s9, 0
	s_add_u32 s14, s8, 0xd132000
	s_addc_u32 s15, s9, 0
	s_add_u32 s16, s8, 0xe3f2000
	s_addc_u32 s17, s9, 0
	s_add_u32 s18, s8, 0xeff2000
	s_addc_u32 s19, s9, 0
	s_add_u32 s20, s8, 0xfbf2000
	s_addc_u32 s21, s9, 0
	s_add_u32 s22, s8, 0xfc52000
	s_addc_u32 s23, s9, 0
	s_add_u32 s24, s8, 0x8752000
	s_addc_u32 s25, s9, 0
	s_add_u32 s26, s8, 0x7b52000
	v_mov_b32_e32 v1, v0
	v_mov_b32_e32 v2, v0
	v_mov_b32_e32 v3, v0
	s_addc_u32 s27, s9, 0
	s_lshl_b32 s39, s2, 2
	s_lshl_b32 s40, s3, 2
	s_movk_i32 s41, 0x800
	s_movk_i32 s42, 0x1000
	s_movk_i32 s43, 0xffef
	s_movk_i32 s44, 0xffdf
	s_movk_i32 s45, 0xffcf
	s_movk_i32 s46, 0x5600
	s_movk_i32 s47, 0xffee
	s_movk_i32 s48, 0xffed
	s_movk_i32 s49, 0xffec
	s_movk_i32 s50, 0xffde
	s_movk_i32 s51, 0xffdd
	s_movk_i32 s52, 0xffdc
	s_movk_i32 s53, 0xffce
	s_movk_i32 s54, 0xffcd
	s_movk_i32 s55, 0xffcc
	s_movk_i32 s56, 0xffeb
	s_movk_i32 s57, 0xffea
	s_movk_i32 s58, 0xffe9
	s_movk_i32 s59, 0xffe8
	s_movk_i32 s60, 0xffe7
	s_movk_i32 s61, 0xffe6
	s_movk_i32 s62, 0xffe5
	s_movk_i32 s63, 0xffe4
	s_movk_i32 s64, 0xffe3
	s_movk_i32 s65, 0xffe2
	s_movk_i32 s66, 0xffe1
	s_movk_i32 s67, 0xffe0
	s_movk_i32 s68, 0x110
	s_movk_i32 s69, 0xfef4
	s_movk_i32 s70, 0x1100
	s_movk_i32 s71, 0x7fff
	v_mbcnt_hi_u32_b32 v97, -1, v175
	v_mov_b32_e32 v204, v73
	v_mov_b32_e32 v205, v73
	v_mov_b32_e32 v200, v73
	v_mov_b32_e32 v201, v73
	v_mov_b32_e32 v202, v73
	v_mov_b32_e32 v203, v73
	s_mov_b32 s72, s2
	s_branch .LBB0_2698

.Lxb_done_10:
.LBB0_2948:
	s_or_b64 exec, exec, s[4:5]
	v_mov_b32_e32 v175, v174
	s_mov_b64 s[42:43], s[82:83]
	s_load_dwordx2 s[6:7], s[90:91], 0x118
	s_mov_b32 s3, 0
	s_waitcnt lgkmcnt(0)
	v_mov_b32_e32 v0, 0
	s_mov_b32 s33, s88
	s_mov_b32 s2, s86
	s_barrier
	s_cmpk_lt_i32 s33, 0x80
	s_cselect_b64 s[4:5], -1, 0
	v_writelane_b32 v252, s4, 7
	s_mov_b64 s[0:1], s[90:91]
	v_mov_b32_e32 v89, 0
	v_writelane_b32 v252, s5, 8
	s_mov_b32 s45, 0
	v_readlane_b32 s8, v252, 9
	v_readlane_b32 s9, v252, 10
	s_add_u32 s2, s42, s8
	s_addc_u32 s8, s43, s9
	s_add_u32 s2, s2, 0x453f800
	v_writelane_b32 v252, s2, 11
	s_addc_u32 s2, s8, 0
	s_add_u32 s74, s42, 0xa432000
	s_addc_u32 s75, s43, 0
	s_add_u32 s55, s42, 0x5d52000
	s_addc_u32 s60, s43, 0
	s_add_u32 s61, s42, 0xa372000
	s_addc_u32 s62, s43, 0
	s_add_u32 s48, s42, 0x4552000
	s_addc_u32 s49, s43, 0
	s_add_u32 s50, s42, 0xb932000
	s_addc_u32 s51, s43, 0
	s_ashr_i32 s63, s3, 31
	s_add_u32 s79, s42, 0x8752000
	s_addc_u32 s80, s43, 0
	s_add_u32 s81, s42, 0xe3f2000
	s_addc_u32 s82, s43, 0
	s_add_u32 s83, s42, 0xeff2000
	s_addc_u32 s95, s43, 0
	s_add_u32 s85, s42, 0x7b52000
	s_addc_u32 s88, s43, 0
	s_add_u32 s89, s42, 0xfbf2000
	s_addc_u32 s46, s43, 0
	s_add_u32 s47, s42, 0xfc52000
	s_addc_u32 s69, s43, 0
	v_writelane_b32 v252, s2, 12
	s_add_u32 s2, s6, 0x3d20000
	v_writelane_b32 v252, s2, 13
	s_addc_u32 s2, s7, 0
	v_writelane_b32 v252, s2, 14
	s_add_u32 s2, s42, 0x3dfc000
	v_writelane_b32 v252, s2, 15
	s_addc_u32 s2, s43, 0
	s_add_u32 s54, s42, 0xad32000
	s_addc_u32 s57, s43, 0
	v_writelane_b32 v252, s2, 16
	s_add_u32 s2, s42, 0xd1f2000
	v_writelane_b32 v252, s2, 17
	s_addc_u32 s2, s43, 0
	s_add_u32 s56, s42, 0x7552000
	s_addc_u32 s58, s43, 0
	v_writelane_b32 v252, s2, 18
	s_add_u32 s2, s42, 0x3dbc000
	v_writelane_b32 v252, s2, 19
	s_addc_u32 s2, s43, 0
	v_writelane_b32 v252, s2, 20
	s_mov_b64 s[8:9], 0
	v_cmp_eq_u32_e64 s[4:5], 0, v175
	v_mov_b32_e32 v1, v0
	v_mov_b32_e32 v2, v0
	v_mov_b32_e32 v3, v0
	s_mov_b64 s[6:7], 8
	v_mov_b32_e32 v176, 1
	v_mov_b32_e32 v177, 0x20008
	s_movk_i32 s59, 0x300
	s_movk_i32 s90, 0xd0
	s_mov_b32 s38, 0x3e16c740
	s_mov_b32 s68, 0xff61b1e6
	s_movk_i32 s91, 0x200
	s_movk_i32 s86, 0x100
	s_movk_i32 s87, 0x800
	s_movk_i32 s92, 0x90
	s_movk_i32 s93, 0x7fff
	s_mov_b32 s2, 0xd7f2000
	s_movk_i32 s39, 0xfeff
	s_mov_b32 s94, 0x4552000
	v_mov_b32_e32 v178, 0x4180
	v_mov_b32_e32 v179, 0x4380
	v_mov_b32_e32 v180, 0x80
	v_mov_b32_e32 v181, 0xf149f2ca
	v_mov_b32_e32 v182, 0x980
	v_mov_b32_e32 v183, 0xb80
	v_writelane_b32 v252, s8, 21
	s_mov_b64 s[14:15], -1
	s_mov_b64 s[52:53], 0x2000
	s_mov_b64 s[96:97], 0x4552200
	v_writelane_b32 v252, s9, 22
	s_branch .LBB0_2950

.Lxb_done_11:
.LBB0_3155:
	s_or_b64 exec, exec, s[4:5]
	v_mov_b32_e32 v74, v174
	s_load_dwordx2 s[18:19], s[0:1], 0x120
	s_waitcnt lgkmcnt(0)
	s_mov_b64 s[2:3], s[88:89]
	s_barrier
	s_add_u32 s16, s18, 0x454c000
	v_mov_b32_e32 v0, 0
	s_mov_b32 s24, 0
	s_mov_b32 s2, s85
	s_mov_b32 s3, s86
	s_addc_u32 s17, s19, 0
	s_cmpk_eq_i32 s3, 0x100
	s_mov_b64 s[4:5], -1
	s_cbranch_scc1 .LBB0_3170
	s_cmpk_gt_i32 s2, 0x6bf
	s_cbranch_scc1 .LBB0_3169
	v_and_b32_e32 v10, 63, v74
	v_mov_b32_e32 v3, 0
	v_lshlrev_b32_e32 v2, 3, v10
	v_lshl_add_u64 v[8:9], s[18:19], 0, v[2:3]
	v_lshlrev_b32_e32 v2, 2, v74
	s_mov_b64 s[4:5], 0x6952000
	s_waitcnt vmcnt(0)
	v_and_b32_e32 v22, 60, v2
	v_lshlrev_b32_e32 v2, 3, v74
	v_lshl_add_u64 v[4:5], v[8:9], 0, s[4:5]
	s_mov_b64 s[4:5], 0x6f52000
	v_and_b32_e32 v14, 56, v2
	v_lshl_add_u64 v[6:7], v[8:9], 0, s[4:5]
	s_mov_b64 s[4:5], 0xcb32000
	v_lshlrev_b32_e32 v2, 1, v14
	v_lshlrev_b32_e32 v20, 2, v10
	v_lshl_add_u64 v[8:9], v[8:9], 0, s[4:5]
	v_cmp_eq_u32_e64 s[4:5], 0, v10
	v_lshl_add_u64 v[10:11], s[18:19], 0, v[2:3]
	s_mov_b64 s[6:7], 0x7552000
	v_ashrrev_i32_e32 v2, 3, v74
	s_movk_i32 s8, 0x6000
	v_lshl_add_u64 v[10:11], v[10:11], 0, s[6:7]
	v_mad_i64_i32 v[12:13], s[6:7], v2, s8, 0
	v_lshlrev_b32_e32 v21, 1, v2
	v_add_u32_e32 v2, 0x200, v74
	v_add_u32_e32 v24, 0x400, v74
	v_add_u32_e32 v25, 0x600, v74
	s_ashr_i32 s25, s24, 31
	v_ashrrev_i32_e32 v16, 3, v2
	v_ashrrev_i32_e32 v18, 3, v24
	v_ashrrev_i32_e32 v26, 3, v25
	v_mul_u32_u24_e32 v23, 0x210, v14
	v_mad_i64_i32 v[14:15], s[6:7], v16, s8, 0
	v_lshlrev_b32_e32 v32, 1, v16
	v_mad_i64_i32 v[16:17], s[6:7], v18, s8, 0
	v_lshlrev_b32_e32 v33, 1, v18
	v_mad_i64_i32 v[18:19], s[6:7], v26, s8, 0
	v_lshlrev_b32_e32 v34, 1, v26
	s_add_u32 s12, s18, 0x4552000
	v_lshlrev_b32_e32 v26, 4, v74
	s_movk_i32 s9, 0x210
	s_addc_u32 s6, s19, 0
	v_and_b32_e32 v38, 0x1f0, v26
	v_ashrrev_i32_e32 v28, 5, v74
	v_ashrrev_i32_e32 v2, 5, v2
	v_ashrrev_i32_e32 v26, 5, v24
	v_ashrrev_i32_e32 v24, 5, v25
	v_ashrrev_i32_e32 v0, 6, v74
	s_and_b32 s13, s6, 0xffff
	v_mul_lo_u32 v35, v28, s9
	v_mul_lo_u32 v36, v2, s9
	v_mul_lo_u32 v37, v26, s9
	v_mul_lo_u32 v39, v24, s9
	s_lshl_b32 s6, s2, 3
	v_lshl_or_b32 v25, s2, 17, v38
	v_ashrrev_i32_e32 v1, 31, v0
	s_mov_b32 s21, 0
	s_mov_b32 s15, 0x20000
	s_brev_b32 s14, -2
	s_add_i32 s20, s6, 0xfffffa00
	s_lshl_b32 s26, s3, 3
	v_lshlrev_b32_e32 v24, 11, v24
	v_or_b32_e32 v25, 0x600, v25
	s_lshl_b32 s27, s3, 17
	v_lshlrev_b32_e32 v26, 11, v26
	v_lshlrev_b32_e32 v27, 11, v2
	v_lshlrev_b32_e32 v28, 11, v28
	s_lshl_b32 s22, s2, 6
	s_lshl_b32 s28, s3, 6
	s_lshl_b32 s29, s2, 4
	s_lshl_b32 s30, s3, 4
	v_lshlrev_b32_e32 v29, 2, v22
	v_mov_b32_e32 v30, 0x358637bd
	s_mov_b32 s31, 0x800000
	v_lshlrev_b32_e32 v2, 1, v20
	v_add_u32_e32 v31, v21, v23
	v_add_u32_e32 v32, v32, v23
	v_add_u32_e32 v33, v33, v23
	v_add_u32_e32 v34, v34, v23
	v_add_u32_e32 v35, v38, v35
	v_add_u32_e32 v36, v38, v36
	v_add_u32_e32 v37, v38, v37
	v_add_u32_e32 v38, v38, v39
	v_mov_b32_e32 v39, 1
	s_mov_b32 s33, s2
	s_branch .LBB0_3159

.Lxb_done_12:
.LBB0_3315:
	s_or_b64 exec, exec, s[4:5]
	v_mov_b32_e32 v59, v174
	s_load_dwordx2 s[10:11], s[0:1], 0x120
	s_mov_b64 s[18:19], s[88:89]
	s_waitcnt lgkmcnt(0)
	s_barrier
	s_add_u32 s16, s10, 0x454f000
	s_mov_b32 s4, 0
	v_mov_b32_e32 v0, 0
	s_mov_b32 s2, s85
	s_mov_b32 s3, s86
	s_addc_u32 s17, s11, 0
	s_cmpk_gt_i32 s2, 0x17f
	v_mov_b32_e32 v57, 0
	s_cbranch_scc1 .LBB0_3338
	s_ashr_i32 s5, s4, 31
	s_add_u32 s8, s0, s4
	s_addc_u32 s9, s1, s5
	s_load_dwordx4 s[4:7], s[8:9], 0x60
	v_and_b32_e32 v2, 63, v59
	s_add_u32 s20, s10, 0x3b40000
	v_lshlrev_b32_e32 v60, 4, v2
	v_mov_b32_e32 v61, v57
	s_addc_u32 s21, s11, 0
	v_lshl_add_u64 v[0:1], s[10:11], 0, v[60:61]
	s_mov_b64 s[14:15], 0xe3f2000
	v_lshlrev_b32_e32 v56, 5, v2
	s_mov_b64 s[8:9], 0x1000
	s_waitcnt lgkmcnt(0)
	s_cmp_lg_u64 s[6:7], 0
	v_lshl_add_u64 v[62:63], v[0:1], 0, s[14:15]
	v_lshl_add_u64 v[0:1], s[4:5], 0, v[56:57]
	s_cselect_b64 s[22:23], -1, 0
	s_add_u32 s6, s6, 0x1000
	v_lshlrev_b32_e32 v58, 3, v2
	v_lshl_add_u64 v[64:65], v[0:1], 0, s[8:9]
	v_lshl_add_u64 v[0:1], s[10:11], 0, v[56:57]
	s_mov_b64 s[4:5], 0x3b42000
	s_addc_u32 s7, s7, 0
	v_lshl_add_u64 v[66:67], v[0:1], 0, s[4:5]
	v_cmp_eq_u32_e64 s[4:5], 0, v2
	v_or_b32_e32 v2, 0x200, v58
	v_lshl_add_u64 v[68:69], s[6:7], 0, v[56:57]
	v_lshlrev_b32_e32 v56, 2, v2
	v_lshl_add_u64 v[70:71], s[6:7], 0, v[56:57]
	s_load_dword s6, s[0:1], 0x134
	s_add_u32 s12, s10, 0x4552000
	s_addc_u32 s13, s11, 0
	v_ashrrev_i32_e32 v3, 4, v59
	s_and_b32 s13, s13, 0xffff
	s_waitcnt lgkmcnt(0)
	s_cmp_eq_u32 s6, 0
	v_lshlrev_b32_e32 v1, 11, v3
	s_cselect_b64 s[6:7], -1, 0
	v_and_b32_e32 v1, 0xffffe000, v1
	v_and_b32_e32 v5, -4, v3
	v_or_b32_e32 v0, 4, v58
	v_or_b32_e32 v4, 0x204, v58
	v_cndmask_b32_e64 v72, 0, 1.0, s[6:7]
	v_lshl_add_u32 v1, s2, 16, v1
	s_movk_i32 s6, 0x1c00
	s_mov_b32 s15, 0x20000
	s_brev_b32 s14, -2
	v_mov_b32_e32 v73, v72
	v_lshl_add_u64 v[74:75], s[18:19], 0, v[60:61]
	v_lshl_add_u32 v76, s2, 5, v5
	s_lshl_b32 s25, s3, 5
	v_or3_b32 v83, v1, v60, s6
	s_lshl_b32 s27, s3, 16
	v_lshlrev_b32_e32 v78, 1, v58
	v_mov_b32_e32 v79, v57
	s_movk_i32 s33, 0xfff
	s_movk_i32 s36, 0x6000
	v_mov_b32_e32 v80, v72
	v_mov_b32_e32 v81, v72
	s_mov_b32 s24, 0x3a800000
	s_mov_b32 s26, 0x358637bd
	v_mov_b32_e32 v82, 0x358637bd
	s_mov_b32 s37, 0x800000
	s_mov_b64 s[28:29], 0x4000
	s_mov_b64 s[30:31], 0x3000
	v_lshlrev_b32_e32 v84, 2, v0
	v_lshlrev_b32_e32 v86, 2, v2
	v_lshlrev_b32_e32 v88, 2, v4
	v_mov_b32_e32 v172, 1
	s_mov_b32 s38, s2
	s_branch .LBB0_3319

.Lxb_done_13:
.LBB0_3471:
	s_or_b64 exec, exec, s[4:5]
	v_mov_b32_e32 v4, v174
	s_load_dwordx2 s[4:5], s[0:1], 0x120
	s_mov_b64 s[2:3], s[88:89]
	s_waitcnt lgkmcnt(0)
	s_barrier
	s_mov_b32 s2, 0
	v_mov_b32_e32 v0, 0
	s_mov_b32 s2, s85
	s_mov_b32 s3, s86
	s_cmpk_lt_i32 s2, 0x100
	s_cselect_b64 s[6:7], -1, 0
	s_cmpk_gt_i32 s2, 0xff
	v_readfirstlane_b32 s33, v4
	s_barrier
	s_cbranch_scc1 .LBB0_3473
	s_ashr_i32 s8, s2, 31
	s_lshr_b32 s8, s8, 29
	s_add_i32 s8, s2, s8
	s_ashr_i32 s9, s8, 3
	s_and_b32 s8, s8, -8
	s_sub_i32 s8, s2, s8
	s_lshr_b32 s10, s8, 31
	s_or_b32 s10, s10, 32
	s_mul_i32 s8, s10, s8
	s_add_i32 s8, s8, s9
	s_ashr_i32 s9, s8, 31
	s_lshr_b32 s9, s9, 27
	s_add_i32 s9, s8, s9
	s_ashr_i32 s10, s9, 5
	s_lshl_b32 s10, s10, 3
	s_sub_i32 s11, 64, s10
	s_min_u32 s11, s11, 8
	s_andn2_b32 s9, s9, 31
	s_sub_i32 s13, s8, s9
	v_cvt_f32_ubyte0_e32 v1, s11
	v_cvt_f32_i32_e32 v0, s13
	v_rcp_iflag_f32_e32 v2, v1
	s_ashr_i32 s8, s13, 30
	s_or_b32 s12, s8, 1
	v_mul_f32_e32 v2, v0, v2
	v_trunc_f32_e32 v2, v2
	v_fma_f32 v0, -v2, v1, v0
	v_cvt_i32_f32_e32 v2, v2
	v_cmp_ge_f32_e64 s[8:9], |v0|, v1
	s_and_b64 s[8:9], s[8:9], exec
	s_cselect_b32 s8, s12, 0
	v_readfirstlane_b32 s9, v2
	s_add_i32 s8, s9, s8
	s_sext_i32_i8 s12, s8
	s_mul_i32 s8, s8, s11
	s_sub_i32 s8, s13, s8
	s_sext_i32_i8 s8, s8
	s_add_i32 s56, s10, s8

.Lxb_done_14:
.LBB0_3562:
	s_or_b64 exec, exec, s[4:5]
	s_load_dwordx2 s[4:5], s[0:1], 0x120
	s_mov_b32 s2, 0
	s_waitcnt lgkmcnt(0)
	v_mov_b32_e32 v0, 0
	s_barrier
	s_cmpk_gt_i32 s85, 0x17f
	v_mov_b32_e32 v17, 0
	s_cbranch_scc1 .LBB0_3565
	s_ashr_i32 s3, s2, 31
	s_add_u32 s0, s0, s2
	s_addc_u32 s1, s1, s3
	v_ashrrev_i32_e32 v0, 4, v174
	s_load_dwordx2 s[0:1], s[0:1], 0x70
	v_and_b32_e32 v1, -4, v0
	v_lshlrev_b32_e32 v0, 3, v174
	v_and_b32_e32 v0, 0x1f8, v0
	v_lshlrev_b32_e32 v16, 1, v0
	v_lshl_add_u64 v[2:3], s[4:5], 0, v[16:17]
	s_mov_b64 s[2:3], 0xbd52000
	v_lshl_add_u64 v[18:19], v[2:3], 0, s[2:3]
	v_lshlrev_b32_e32 v2, 2, v0
	v_mov_b32_e32 v3, v17
	s_waitcnt lgkmcnt(0)
	v_lshl_add_u64 v[4:5], s[0:1], 0, v[2:3]
	s_mov_b64 s[0:1], 0x1000
	v_lshl_add_u64 v[20:21], v[4:5], 0, s[0:1]
	v_lshl_add_u64 v[2:3], s[4:5], 0, v[2:3]
	s_mov_b64 s[0:1], 0x3b45000
	v_lshl_add_u64 v[22:23], v[2:3], 0, s[0:1]
	v_readlane_b32 s0, v252, 6
	s_cmp_eq_u32 s0, 0
	s_cselect_b64 s[0:1], -1, 0
	v_cndmask_b32_e64 v24, 0, 1.0, s[0:1]
	s_mov_b32 s0, 0x358637bd
	v_mov_b32_e32 v25, v24
	v_lshl_add_u64 v[26:27], s[88:89], 0, v[16:17]
	v_lshl_add_u32 v28, s85, 5, v1
	s_lshl_b32 s2, s86, 5
	v_lshlrev_b32_e32 v30, 1, v0
	v_mov_b32_e32 v31, v17
	s_movk_i32 s3, 0xfff
	s_movk_i32 s9, 0x6000
	v_mov_b32_e32 v32, v24
	v_mov_b32_e32 v33, v24
	s_mov_b32 s8, 0x3a800000
	v_mov_b64_e32 v[34:35], s[0:1]
	s_mov_b32 s10, 0x800000
	v_lshlrev_b32_e32 v36, 2, v0
	v_mov_b32_e32 v37, v17
